# st loop v2: unmasked packed decay math off-diagonal, masked on diagonal
# speedup vs baseline: 1.0107x; 1.0012x over previous
.LBB0_820:
	s_cmp_eq_u32 s7, 1
	s_cbranch_scc1 .Lst_diag
	ds_read_b128 v[246:249], v179 offset:0
	ds_read_b128 v[184:187], v179 offset:512
	ds_read_b64 v[196:197], v179 offset:32
	ds_read_b64 v[250:251], v179 offset:40
	ds_read_b128 v[188:191], v179 offset:544
	v_lshrrev_b32_e32 v177, 3, v180
	s_waitcnt lgkmcnt(8)
	v_mfma_f32_32x32x16_bf16 v[32:47], v[96:99], v[112:115], 0
	ds_read_b128 v[96:99], v183 offset:128
	s_waitcnt lgkmcnt(5)
	v_pk_add_f32 v[246:247], v[246:247], v[178:179] op_sel_hi:[1,0] neg_lo:[0,1] neg_hi:[0,1]
	v_pk_add_f32 v[248:249], v[248:249], v[178:179] op_sel_hi:[1,0] neg_lo:[0,1] neg_hi:[0,1]
	v_pk_mul_f32 v[246:247], v[246:247], s[78:79] op_sel_hi:[1,0]
	v_pk_mul_f32 v[248:249], v[248:249], s[78:79] op_sel_hi:[1,0]
	v_mfma_f32_32x32x16_bf16 v[32:47], v[100:103], v[116:119], v[32:47]
	ds_read_b128 v[100:103], v183 offset:160
	v_exp_f32_e32 v246, v246
	v_exp_f32_e32 v247, v247
	v_exp_f32_e32 v248, v248
	v_exp_f32_e32 v249, v249
	v_mfma_f32_32x32x16_bf16 v[32:47], v[104:107], v[124:127], v[32:47]
	ds_read_b128 v[104:107], v183 offset:192
	s_waitcnt lgkmcnt(6)
	v_pk_mul_f32 v[184:185], v[184:185], v[246:247]
	v_pk_mul_f32 v[186:187], v[186:187], v[248:249]
	ds_read_b128 v[246:249], v179 offset:64
	ds_read_b128 v[192:195], v179 offset:576
	s_waitcnt lgkmcnt(6)
	v_pk_add_f32 v[196:197], v[196:197], v[178:179] op_sel_hi:[1,0] neg_lo:[0,1] neg_hi:[0,1]
	v_pk_add_f32 v[250:251], v[250:251], v[178:179] op_sel_hi:[1,0] neg_lo:[0,1] neg_hi:[0,1]
	v_mfma_f32_32x32x16_bf16 v[32:47], v[108:111], v[128:131], v[32:47]
	ds_read_b128 v[108:111], v183 offset:224
	v_pk_mul_f32 v[196:197], v[196:197], s[78:79] op_sel_hi:[1,0]
	v_pk_mul_f32 v[250:251], v[250:251], s[78:79] op_sel_hi:[1,0]
	v_exp_f32_e32 v196, v196
	v_exp_f32_e32 v197, v197
	s_waitcnt lgkmcnt(5)
	v_mfma_f32_32x32x16_bf16 v[32:47], v[96:99], v[132:135], v[32:47]
	v_xor_b32_e32 v96, v177, v181
	v_and_b32_e32 v96, 15, v96
	v_lshl_add_u32 v96, v96, 4, v182
	v_add_u32_e32 v98, 1, v177
	v_xor_b32_e32 v98, v98, v181
	v_and_b32_e32 v98, 15, v98
	v_lshl_add_u32 v98, v98, 4, v182
	ds_read_b64 v[96:97], v96
	ds_read_b64 v[98:99], v98
	v_exp_f32_e32 v250, v250
	v_exp_f32_e32 v251, v251
	v_pk_mul_f32 v[188:189], v[188:189], v[196:197]
	v_pk_mul_f32 v[190:191], v[190:191], v[250:251]
	s_waitcnt lgkmcnt(6)
	v_mfma_f32_32x32x16_bf16 v[32:47], v[100:103], v[136:139], v[32:47]
	v_add_u32_e32 v100, 2, v177
	v_xor_b32_e32 v100, v100, v181
	v_and_b32_e32 v100, 15, v100
	v_lshl_add_u32 v100, v100, 4, v182
	v_add_u32_e32 v102, 3, v177
	v_xor_b32_e32 v102, v102, v181
	v_and_b32_e32 v102, 15, v102
	v_lshl_add_u32 v102, v102, 4, v182
	ds_read_b64 v[100:101], v100
	ds_read_b64 v[102:103], v102
	ds_read_b64 v[196:197], v179 offset:96
	ds_read_b64 v[250:251], v179 offset:104
	ds_read_b128 v[242:245], v179 offset:608
	s_waitcnt lgkmcnt(9)
	v_pk_add_f32 v[246:247], v[246:247], v[178:179] op_sel_hi:[1,0] neg_lo:[0,1] neg_hi:[0,1]
	v_pk_add_f32 v[248:249], v[248:249], v[178:179] op_sel_hi:[1,0] neg_lo:[0,1] neg_hi:[0,1]
	v_pk_mul_f32 v[246:247], v[246:247], s[78:79] op_sel_hi:[1,0]
	v_pk_mul_f32 v[248:249], v[248:249], s[78:79] op_sel_hi:[1,0]
	v_mfma_f32_32x32x16_bf16 v[32:47], v[104:107], v[140:143], v[32:47]
	v_exp_f32_e32 v246, v246
	v_exp_f32_e32 v247, v247
	v_exp_f32_e32 v248, v248
	v_exp_f32_e32 v249, v249
	s_waitcnt lgkmcnt(7)
	v_mfma_f32_32x32x16_bf16 v[32:47], v[108:111], v[120:123], v[32:47]
	v_pk_mul_f32 v[192:193], v[192:193], v[246:247]
	v_pk_mul_f32 v[194:195], v[194:195], v[248:249]
	s_waitcnt lgkmcnt(1)
	v_pk_add_f32 v[196:197], v[196:197], v[178:179] op_sel_hi:[1,0] neg_lo:[0,1] neg_hi:[0,1]
	v_pk_add_f32 v[250:251], v[250:251], v[178:179] op_sel_hi:[1,0] neg_lo:[0,1] neg_hi:[0,1]
	v_pk_mul_f32 v[196:197], v[196:197], s[78:79] op_sel_hi:[1,0]
	v_pk_mul_f32 v[250:251], v[250:251], s[78:79] op_sel_hi:[1,0]
	v_exp_f32_e32 v196, v196
	v_exp_f32_e32 v197, v197
	v_exp_f32_e32 v250, v250
	v_exp_f32_e32 v251, v251
	s_waitcnt lgkmcnt(0)
	v_pk_mul_f32 v[242:243], v[242:243], v[196:197]
	v_pk_mul_f32 v[244:245], v[244:245], v[250:251]
	s_nop 2
	v_pk_mul_f32 v[32:33], v[32:33], v[184:185]
	v_pk_mul_f32 v[34:35], v[34:35], v[186:187]
	v_pk_mul_f32 v[36:37], v[36:37], v[188:189]
	v_pk_mul_f32 v[38:39], v[38:39], v[190:191]
	v_pk_mul_f32 v[40:41], v[40:41], v[192:193]
	v_pk_mul_f32 v[42:43], v[42:43], v[194:195]
	v_pk_mul_f32 v[44:45], v[44:45], v[242:243]
	v_pk_mul_f32 v[46:47], v[46:47], v[244:245]
	v_cvt_pk_bf16_f32 v32, v32, v33
	v_cvt_pk_bf16_f32 v33, v34, v35
	v_cvt_pk_bf16_f32 v34, v36, v37
	v_cvt_pk_bf16_f32 v35, v38, v39
	v_cvt_pk_bf16_f32 v36, v40, v41
	v_cvt_pk_bf16_f32 v37, v42, v43
	v_cvt_pk_bf16_f32 v38, v44, v45
	v_cvt_pk_bf16_f32 v39, v46, v47
	v_add_u32_e32 v183, 0x2200, v183
	v_add_u32_e32 v179, 0x80, v179
	v_mfma_f32_32x32x16_bf16 v[16:31], v[32:35], v[96:99], v[16:31]
	v_add_u32_e32 v180, 32, v180
	v_mfma_f32_32x32x16_bf16 v[16:31], v[36:39], v[100:103], v[16:31]
	ds_read_b128 v[96:99], v183 offset:0
	ds_read_b128 v[100:103], v183 offset:32
	ds_read_b128 v[104:107], v183 offset:64
	ds_read_b128 v[108:111], v183 offset:96
	s_add_i32 s7, s7, -1
	s_branch .LBB0_820
.Lst_diag:
	ds_read_b128 v[246:249], v179 offset:0
	ds_read_b128 v[184:187], v179 offset:512
	ds_read_b64 v[196:197], v179 offset:32
	ds_read_b64 v[250:251], v179 offset:40
	ds_read_b128 v[188:191], v179 offset:544
	v_lshrrev_b32_e32 v177, 3, v180
	s_waitcnt lgkmcnt(8)
	v_mfma_f32_32x32x16_bf16 v[32:47], v[96:99], v[112:115], 0
	ds_read_b128 v[96:99], v183 offset:128
	v_cmp_le_i32_e32 vcc, v180, v176
	s_waitcnt lgkmcnt(5)
	v_sub_f32_e32 v246, v178, v246
	v_mul_f32_e32 v246, 0x3fb8aa3b, v246
	v_cndmask_b32_e32 v246, v239, v246, vcc
	v_exp_f32_e32 v246, v246
	v_add_u32_e32 v241, 1, v180
	v_mfma_f32_32x32x16_bf16 v[32:47], v[100:103], v[116:119], v[32:47]
	ds_read_b128 v[100:103], v183 offset:160
	v_cmp_le_i32_e32 vcc, v241, v176
	s_waitcnt lgkmcnt(5)
	v_mul_f32_e32 v184, v184, v246
	v_sub_f32_e32 v247, v178, v247
	v_mul_f32_e32 v247, 0x3fb8aa3b, v247
	v_cndmask_b32_e32 v247, v239, v247, vcc
	v_exp_f32_e32 v247, v247
	v_mfma_f32_32x32x16_bf16 v[32:47], v[104:107], v[124:127], v[32:47]
	ds_read_b128 v[104:107], v183 offset:192
	v_add_u32_e32 v241, 2, v180
	v_cmp_le_i32_e32 vcc, v241, v176
	v_mul_f32_e32 v185, v185, v247
	v_sub_f32_e32 v248, v178, v248
	v_mul_f32_e32 v248, 0x3fb8aa3b, v248
	v_cndmask_b32_e32 v248, v239, v248, vcc
	v_mfma_f32_32x32x16_bf16 v[32:47], v[108:111], v[128:131], v[32:47]
	ds_read_b128 v[108:111], v183 offset:224
	v_exp_f32_e32 v248, v248
	v_add_u32_e32 v241, 3, v180
	v_cmp_le_i32_e32 vcc, v241, v176
	v_mul_f32_e32 v186, v186, v248
	v_sub_f32_e32 v249, v178, v249
	v_mul_f32_e32 v249, 0x3fb8aa3b, v249
	s_waitcnt lgkmcnt(3)
	v_mfma_f32_32x32x16_bf16 v[32:47], v[96:99], v[132:135], v[32:47]
	v_xor_b32_e32 v96, v177, v181
	v_and_b32_e32 v96, 15, v96
	v_lshl_add_u32 v96, v96, 4, v182
	v_add_u32_e32 v98, 1, v177
	v_xor_b32_e32 v98, v98, v181
	v_and_b32_e32 v98, 15, v98
	v_lshl_add_u32 v98, v98, 4, v182
	ds_read_b64 v[96:97], v96
	ds_read_b64 v[98:99], v98
	v_cndmask_b32_e32 v249, v239, v249, vcc
	v_exp_f32_e32 v249, v249
	v_add_u32_e32 v241, 8, v180
	v_cmp_le_i32_e32 vcc, v241, v176
	v_mul_f32_e32 v187, v187, v249
	ds_read_b128 v[246:249], v179 offset:64
	ds_read_b128 v[192:195], v179 offset:576
	v_sub_f32_e32 v196, v178, v196
	s_waitcnt lgkmcnt(6)
	v_mfma_f32_32x32x16_bf16 v[32:47], v[100:103], v[136:139], v[32:47]
	v_add_u32_e32 v100, 2, v177
	v_xor_b32_e32 v100, v100, v181
	v_and_b32_e32 v100, 15, v100
	v_lshl_add_u32 v100, v100, 4, v182
	v_add_u32_e32 v102, 3, v177
	v_xor_b32_e32 v102, v102, v181
	v_and_b32_e32 v102, 15, v102
	v_lshl_add_u32 v102, v102, 4, v182
	ds_read_b64 v[100:101], v100
	ds_read_b64 v[102:103], v102
	v_mul_f32_e32 v196, 0x3fb8aa3b, v196
	v_cndmask_b32_e32 v196, v239, v196, vcc
	v_exp_f32_e32 v196, v196
	v_add_u32_e32 v241, 9, v180
	v_cmp_le_i32_e32 vcc, v241, v176
	v_mul_f32_e32 v188, v188, v196
	s_waitcnt lgkmcnt(7)
	v_mfma_f32_32x32x16_bf16 v[32:47], v[104:107], v[140:143], v[32:47]
	v_sub_f32_e32 v197, v178, v197
	v_mul_f32_e32 v197, 0x3fb8aa3b, v197
	v_cndmask_b32_e32 v197, v239, v197, vcc
	v_exp_f32_e32 v197, v197
	v_add_u32_e32 v241, 10, v180
	v_cmp_le_i32_e32 vcc, v241, v176
	s_waitcnt lgkmcnt(6)
	v_mfma_f32_32x32x16_bf16 v[32:47], v[108:111], v[120:123], v[32:47]
	v_mul_f32_e32 v189, v189, v197
	v_sub_f32_e32 v250, v178, v250
	v_mul_f32_e32 v250, 0x3fb8aa3b, v250
	v_cndmask_b32_e32 v250, v239, v250, vcc
	v_exp_f32_e32 v250, v250
	v_add_u32_e32 v241, 11, v180
	v_cmp_le_i32_e32 vcc, v241, v176
	v_mul_f32_e32 v190, v190, v250
	v_sub_f32_e32 v251, v178, v251
	v_mul_f32_e32 v251, 0x3fb8aa3b, v251
	v_cndmask_b32_e32 v251, v239, v251, vcc
	v_exp_f32_e32 v251, v251
	v_add_u32_e32 v241, 16, v180
	v_cmp_le_i32_e32 vcc, v241, v176
	v_mul_f32_e32 v191, v191, v251
	ds_read_b64 v[196:197], v179 offset:96
	ds_read_b64 v[250:251], v179 offset:104
	ds_read_b128 v[242:245], v179 offset:608
	s_waitcnt lgkmcnt(6)
	v_sub_f32_e32 v246, v178, v246
	v_mul_f32_e32 v246, 0x3fb8aa3b, v246
	v_cndmask_b32_e32 v246, v239, v246, vcc
	v_exp_f32_e32 v246, v246
	v_add_u32_e32 v241, 17, v180
	v_cmp_le_i32_e32 vcc, v241, v176
	s_waitcnt lgkmcnt(5)
	v_mul_f32_e32 v192, v192, v246
	v_sub_f32_e32 v247, v178, v247
	v_mul_f32_e32 v247, 0x3fb8aa3b, v247
	v_cndmask_b32_e32 v247, v239, v247, vcc
	v_exp_f32_e32 v247, v247
	v_add_u32_e32 v241, 18, v180
	v_cmp_le_i32_e32 vcc, v241, v176
	v_mul_f32_e32 v193, v193, v247
	v_sub_f32_e32 v248, v178, v248
	v_mul_f32_e32 v248, 0x3fb8aa3b, v248
	v_cndmask_b32_e32 v248, v239, v248, vcc
	v_exp_f32_e32 v248, v248
	v_add_u32_e32 v241, 19, v180
	v_cmp_le_i32_e32 vcc, v241, v176
	v_mul_f32_e32 v194, v194, v248
	v_sub_f32_e32 v249, v178, v249
	v_mul_f32_e32 v249, 0x3fb8aa3b, v249
	v_cndmask_b32_e32 v249, v239, v249, vcc
	v_exp_f32_e32 v249, v249
	v_add_u32_e32 v241, 24, v180
	v_cmp_le_i32_e32 vcc, v241, v176
	v_mul_f32_e32 v195, v195, v249
	s_waitcnt lgkmcnt(1)
	v_sub_f32_e32 v196, v178, v196
	v_mul_f32_e32 v196, 0x3fb8aa3b, v196
	v_cndmask_b32_e32 v196, v239, v196, vcc
	v_exp_f32_e32 v196, v196
	v_add_u32_e32 v241, 25, v180
	v_cmp_le_i32_e32 vcc, v241, v176
	s_waitcnt lgkmcnt(0)
	v_mul_f32_e32 v242, v242, v196
	v_sub_f32_e32 v197, v178, v197
	v_mul_f32_e32 v197, 0x3fb8aa3b, v197
	v_cndmask_b32_e32 v197, v239, v197, vcc
	v_exp_f32_e32 v197, v197
	v_add_u32_e32 v241, 26, v180
	v_cmp_le_i32_e32 vcc, v241, v176
	v_mul_f32_e32 v243, v243, v197
	v_sub_f32_e32 v250, v178, v250
	v_mul_f32_e32 v250, 0x3fb8aa3b, v250
	v_cndmask_b32_e32 v250, v239, v250, vcc
	v_exp_f32_e32 v250, v250
	v_add_u32_e32 v241, 27, v180
	v_cmp_le_i32_e32 vcc, v241, v176
	v_mul_f32_e32 v244, v244, v250
	v_sub_f32_e32 v251, v178, v251
	v_mul_f32_e32 v251, 0x3fb8aa3b, v251
	v_cndmask_b32_e32 v251, v239, v251, vcc
	v_exp_f32_e32 v251, v251
	s_nop 0
	v_mul_f32_e32 v245, v245, v251
	v_mul_f32_e32 v32, v32, v184
	v_mul_f32_e32 v33, v33, v185
	v_mul_f32_e32 v34, v34, v186
	v_mul_f32_e32 v35, v35, v187
	v_mul_f32_e32 v36, v36, v188
	v_mul_f32_e32 v37, v37, v189
	v_mul_f32_e32 v38, v38, v190
	v_mul_f32_e32 v39, v39, v191
	v_mul_f32_e32 v40, v40, v192
	v_mul_f32_e32 v41, v41, v193
	v_mul_f32_e32 v42, v42, v194
	v_mul_f32_e32 v43, v43, v195
	v_mul_f32_e32 v44, v44, v242
	v_mul_f32_e32 v45, v45, v243
	v_mul_f32_e32 v46, v46, v244
	v_mul_f32_e32 v47, v47, v245
	v_cvt_pk_bf16_f32 v32, v32, v33
	v_cvt_pk_bf16_f32 v33, v34, v35
	v_cvt_pk_bf16_f32 v34, v36, v37
	v_cvt_pk_bf16_f32 v35, v38, v39
	v_cvt_pk_bf16_f32 v36, v40, v41
	v_cvt_pk_bf16_f32 v37, v42, v43
	v_cvt_pk_bf16_f32 v38, v44, v45
	v_cvt_pk_bf16_f32 v39, v46, v47
	v_add_u32_e32 v183, 0x2200, v183
	v_add_u32_e32 v179, 0x80, v179
	v_mfma_f32_32x32x16_bf16 v[16:31], v[32:35], v[96:99], v[16:31]
	v_add_u32_e32 v180, 32, v180
	v_mfma_f32_32x32x16_bf16 v[16:31], v[36:39], v[100:103], v[16:31]
